# attention block epilogue: O tile transposed through wave-private LDS and stored as 8 dwordx4 per lane instead of 64 half-masked dword stores
# speedup vs baseline: 1.0100x; 1.0074x over previous
; #define SBAR() __builtin_amdgcn_sched_barrier(0)
; __device__ __forceinline__ int crow(int r, int hi) { return (r & 3) + 8 * (r >> 2) + 4 * hi; }
; __device__ __forceinline__ unsigned cvtpk(float lo, float hi) { return pg8::cvt_pk_bf16(lo, hi); }
; #define SEAM_K0() do { VMWN(NQL); SWRITE_HK(0); SBAR(); } while (0)
; __device__ __forceinline__ void attn_block(const BlockRef& cur, const BlockRef& nxt, char* lds, Seam& S) {
;     ...
;     SBAR(); SEAM_K0();
;     if (hi == 0) li_l[r32] = l_reg; asm volatile("s_waitcnt lgkmcnt(0)" ::: "memory");
;     float rli[16];
; #pragma unroll
;     for (int r = 0; r < 16; ++r) rli[r] = __builtin_amdgcn_rcpf(li_l[crow(r, hi)]);
;     bf16* Ow = cur.O + (size_t)(wid * QBLK) * D;
; #pragma unroll
;     for (int r = 0; r < 16; ++r) { const int orow = crow(r, hi);
; #pragma unroll
;         for (int d0 = 0; d0 < 4; ++d0) { const float v = o[d0][r] * rli[r];
;             const float vn = __shfl_xor(v, 1);
;             if ((r32 & 1) == 0) __builtin_nontemporal_store(cvtpk(v, vn), (unsigned*)(Ow + (size_t)orow * D + d0 * 32 + r32)); } }
.LBB0_351:
	s_waitcnt vmcnt(8)
	s_waitcnt vmcnt(9)
	ds_write_b128 v226, v[104:107] offset:32768
	s_waitcnt vmcnt(8)
	ds_write_b128 v226, v[108:111] offset:40960
	s_and_saveexec_b64 s[40:41], s[38:39]
	ds_write_b32 v227, v112
	s_or_b64 exec, exec, s[40:41]
	s_waitcnt lgkmcnt(0)
	v_add_u32_e32 v64, s69, v200
	ds_read_b128 v[76:79], v64
	ds_read_b128 v[72:75], v64 offset:32
	ds_read_b128 v[68:71], v64 offset:64
	ds_read_b128 v[64:67], v64 offset:96
	s_mul_i32 s40, s68, 0x120
	s_add_i32 s40, s40, 0x11000
	s_mov_b32 s38, s68
	s_ashr_i32 s39, s68, 31
	s_lshl_b64 s[38:39], s[38:39], 8
	s_add_u32 s38, s22, s38
	s_addc_u32 s39, s23, s39
	s_movk_i32 s41, 0x480
	s_movk_i32 s68, 0x23e
	s_movk_i32 s69, 0x120
	s_mov_b64 s[42:43], 0x1000
	v_and_b32_e32 v80, 1, v205
	v_cmp_eq_u32_e32 vcc, 0, v80
	v_lshlrev_b32_e32 v122, 1, v223
	v_mad_u32_u24 v122, v224, s41, v122
	v_mad_u32_u24 v122, v80, s68, v122
	v_add_u32_e32 v122, s40, v122
	v_lshrrev_b32_e32 v123, 4, v205
	v_and_b32_e32 v81, 15, v205
	v_lshlrev_b32_e32 v81, 4, v81
	v_mad_u32_u24 v123, v123, s69, v81
	v_add_u32_e32 v123, s40, v123
	v_lshlrev_b32_e32 v126, 4, v205
	v_mov_b32_e32 v127, 0
	v_lshl_add_u64 v[124:125], s[38:39], 0, v[126:127]
	v_lshl_add_u64 v[126:127], v[124:125], 0, s[42:43]
	s_waitcnt lgkmcnt(0)
	v_rcp_f32_e32 v76, v76
	v_rcp_f32_e32 v77, v77
	v_rcp_f32_e32 v78, v78
	v_rcp_f32_e32 v79, v79
	v_rcp_f32_e32 v72, v72
	v_rcp_f32_e32 v73, v73
	v_rcp_f32_e32 v74, v74
	v_rcp_f32_e32 v75, v75
	v_rcp_f32_e32 v68, v68
	v_rcp_f32_e32 v69, v69
	v_rcp_f32_e32 v70, v70
	v_rcp_f32_e32 v71, v71
	v_rcp_f32_e32 v64, v64
	v_rcp_f32_e32 v65, v65
	v_rcp_f32_e32 v66, v66
	v_rcp_f32_e32 v67, v67
	s_nop 0
	v_mul_f32_e32 v104, v0, v76
	v_mul_f32_e32 v105, v2, v78
	v_mul_f32_e32 v106, v1, v77
	v_mul_f32_e32 v107, v3, v79
	v_mov_b32_dpp v108, v104 quad_perm:[1,0,3,2] row_mask:0xf bank_mask:0xf
	v_mov_b32_dpp v109, v105 quad_perm:[1,0,3,2] row_mask:0xf bank_mask:0xf
	v_mov_b32_dpp v110, v106 quad_perm:[1,0,3,2] row_mask:0xf bank_mask:0xf
	v_mov_b32_dpp v111, v107 quad_perm:[1,0,3,2] row_mask:0xf bank_mask:0xf
	v_cndmask_b32_e32 v112, v109, v104, vcc
	v_cndmask_b32_e32 v113, v105, v108, vcc
	v_cndmask_b32_e32 v114, v111, v106, vcc
	v_cndmask_b32_e32 v115, v107, v110, vcc
	v_cvt_pk_bf16_f32 v116, v112, v113
	v_cvt_pk_bf16_f32 v117, v114, v115
	ds_write_b32 v122, v116
	ds_write_b32 v122, v117 offset:288
	v_mul_f32_e32 v104, v4, v72
	v_mul_f32_e32 v105, v6, v74
	v_mul_f32_e32 v106, v5, v73
	v_mul_f32_e32 v107, v7, v75
	v_mov_b32_dpp v108, v104 quad_perm:[1,0,3,2] row_mask:0xf bank_mask:0xf
	v_mov_b32_dpp v109, v105 quad_perm:[1,0,3,2] row_mask:0xf bank_mask:0xf
	v_mov_b32_dpp v110, v106 quad_perm:[1,0,3,2] row_mask:0xf bank_mask:0xf
	v_mov_b32_dpp v111, v107 quad_perm:[1,0,3,2] row_mask:0xf bank_mask:0xf
	v_cndmask_b32_e32 v112, v109, v104, vcc
	v_cndmask_b32_e32 v113, v105, v108, vcc
	v_cndmask_b32_e32 v114, v111, v106, vcc
	v_cndmask_b32_e32 v115, v107, v110, vcc
	v_cvt_pk_bf16_f32 v116, v112, v113
	v_cvt_pk_bf16_f32 v117, v114, v115
	ds_write_b32 v122, v116 offset:2304
	ds_write_b32 v122, v117 offset:2592
	v_mul_f32_e32 v104, v8, v68
	v_mul_f32_e32 v105, v10, v70
	v_mul_f32_e32 v106, v9, v69
	v_mul_f32_e32 v107, v11, v71
	v_mov_b32_dpp v108, v104 quad_perm:[1,0,3,2] row_mask:0xf bank_mask:0xf
	v_mov_b32_dpp v109, v105 quad_perm:[1,0,3,2] row_mask:0xf bank_mask:0xf
	v_mov_b32_dpp v110, v106 quad_perm:[1,0,3,2] row_mask:0xf bank_mask:0xf
	v_mov_b32_dpp v111, v107 quad_perm:[1,0,3,2] row_mask:0xf bank_mask:0xf
	v_cndmask_b32_e32 v112, v109, v104, vcc
	v_cndmask_b32_e32 v113, v105, v108, vcc
	v_cndmask_b32_e32 v114, v111, v106, vcc
	v_cndmask_b32_e32 v115, v107, v110, vcc
	v_cvt_pk_bf16_f32 v116, v112, v113
	v_cvt_pk_bf16_f32 v117, v114, v115
	ds_write_b32 v122, v116 offset:4608
	ds_write_b32 v122, v117 offset:4896
	v_mul_f32_e32 v104, v12, v64
	v_mul_f32_e32 v105, v14, v66
	v_mul_f32_e32 v106, v13, v65
	v_mul_f32_e32 v107, v15, v67
	v_mov_b32_dpp v108, v104 quad_perm:[1,0,3,2] row_mask:0xf bank_mask:0xf
	v_mov_b32_dpp v109, v105 quad_perm:[1,0,3,2] row_mask:0xf bank_mask:0xf
	v_mov_b32_dpp v110, v106 quad_perm:[1,0,3,2] row_mask:0xf bank_mask:0xf
	v_mov_b32_dpp v111, v107 quad_perm:[1,0,3,2] row_mask:0xf bank_mask:0xf
	v_cndmask_b32_e32 v112, v109, v104, vcc
	v_cndmask_b32_e32 v113, v105, v108, vcc
	v_cndmask_b32_e32 v114, v111, v106, vcc
	v_cndmask_b32_e32 v115, v107, v110, vcc
	v_cvt_pk_bf16_f32 v116, v112, v113
	v_cvt_pk_bf16_f32 v117, v114, v115
	ds_write_b32 v122, v116 offset:6912
	ds_write_b32 v122, v117 offset:7200
	v_mul_f32_e32 v104, v48, v76
	v_mul_f32_e32 v105, v50, v78
	v_mul_f32_e32 v106, v49, v77
	v_mul_f32_e32 v107, v51, v79
	v_mov_b32_dpp v108, v104 quad_perm:[1,0,3,2] row_mask:0xf bank_mask:0xf
	v_mov_b32_dpp v109, v105 quad_perm:[1,0,3,2] row_mask:0xf bank_mask:0xf
	v_mov_b32_dpp v110, v106 quad_perm:[1,0,3,2] row_mask:0xf bank_mask:0xf
	v_mov_b32_dpp v111, v107 quad_perm:[1,0,3,2] row_mask:0xf bank_mask:0xf
	v_cndmask_b32_e32 v112, v109, v104, vcc
	v_cndmask_b32_e32 v113, v105, v108, vcc
	v_cndmask_b32_e32 v114, v111, v106, vcc
	v_cndmask_b32_e32 v115, v107, v110, vcc
	v_cvt_pk_bf16_f32 v116, v112, v113
	v_cvt_pk_bf16_f32 v117, v114, v115
	ds_write_b32 v122, v116 offset:64
	ds_write_b32 v122, v117 offset:352
	v_mul_f32_e32 v104, v52, v72
	v_mul_f32_e32 v105, v54, v74
	v_mul_f32_e32 v106, v53, v73
	v_mul_f32_e32 v107, v55, v75
	v_mov_b32_dpp v108, v104 quad_perm:[1,0,3,2] row_mask:0xf bank_mask:0xf
	v_mov_b32_dpp v109, v105 quad_perm:[1,0,3,2] row_mask:0xf bank_mask:0xf
	v_mov_b32_dpp v110, v106 quad_perm:[1,0,3,2] row_mask:0xf bank_mask:0xf
	v_mov_b32_dpp v111, v107 quad_perm:[1,0,3,2] row_mask:0xf bank_mask:0xf
; __device__ __forceinline__ int crow(int r, int hi) { return (r & 3) + 8 * (r >> 2) + 4 * hi; }
; __device__ __forceinline__ unsigned cvtpk(float lo, float hi) { return pg8::cvt_pk_bf16(lo, hi); }
; __device__ __forceinline__ void attn_block(const BlockRef& cur, const BlockRef& nxt, char* lds, Seam& S) {
;     ...
;     bf16* Ow = cur.O + (size_t)(wid * QBLK) * D;
; #pragma unroll
;     for (int r = 0; r < 16; ++r) { const int orow = crow(r, hi);
; #pragma unroll
;         for (int d0 = 0; d0 < 4; ++d0) { const float v = o[d0][r] * rli[r];
;             const float vn = __shfl_xor(v, 1);
;             if ((r32 & 1) == 0) __builtin_nontemporal_store(cvtpk(v, vn), (unsigned*)(Ow + (size_t)orow * D + d0 * 32 + r32)); } }
	v_cndmask_b32_e32 v112, v109, v104, vcc
	v_cndmask_b32_e32 v113, v105, v108, vcc
	v_cndmask_b32_e32 v114, v111, v106, vcc
	v_cndmask_b32_e32 v115, v107, v110, vcc
	v_cvt_pk_bf16_f32 v116, v112, v113
	v_cvt_pk_bf16_f32 v117, v114, v115
	ds_write_b32 v122, v116 offset:2368
	ds_write_b32 v122, v117 offset:2656
	v_mul_f32_e32 v104, v56, v68
	v_mul_f32_e32 v105, v58, v70
	v_mul_f32_e32 v106, v57, v69
	v_mul_f32_e32 v107, v59, v71
	v_mov_b32_dpp v108, v104 quad_perm:[1,0,3,2] row_mask:0xf bank_mask:0xf
	v_mov_b32_dpp v109, v105 quad_perm:[1,0,3,2] row_mask:0xf bank_mask:0xf
	v_mov_b32_dpp v110, v106 quad_perm:[1,0,3,2] row_mask:0xf bank_mask:0xf
	v_mov_b32_dpp v111, v107 quad_perm:[1,0,3,2] row_mask:0xf bank_mask:0xf
	v_cndmask_b32_e32 v112, v109, v104, vcc
	v_cndmask_b32_e32 v113, v105, v108, vcc
	v_cndmask_b32_e32 v114, v111, v106, vcc
	v_cndmask_b32_e32 v115, v107, v110, vcc
	v_cvt_pk_bf16_f32 v116, v112, v113
	v_cvt_pk_bf16_f32 v117, v114, v115
	ds_write_b32 v122, v116 offset:4672
	ds_write_b32 v122, v117 offset:4960
	v_mul_f32_e32 v104, v60, v64
	v_mul_f32_e32 v105, v62, v66
	v_mul_f32_e32 v106, v61, v65
	v_mul_f32_e32 v107, v63, v67
	v_mov_b32_dpp v108, v104 quad_perm:[1,0,3,2] row_mask:0xf bank_mask:0xf
	v_mov_b32_dpp v109, v105 quad_perm:[1,0,3,2] row_mask:0xf bank_mask:0xf
	v_mov_b32_dpp v110, v106 quad_perm:[1,0,3,2] row_mask:0xf bank_mask:0xf
	v_mov_b32_dpp v111, v107 quad_perm:[1,0,3,2] row_mask:0xf bank_mask:0xf
	v_cndmask_b32_e32 v112, v109, v104, vcc
	v_cndmask_b32_e32 v113, v105, v108, vcc
	v_cndmask_b32_e32 v114, v111, v106, vcc
	v_cndmask_b32_e32 v115, v107, v110, vcc
	v_cvt_pk_bf16_f32 v116, v112, v113
	v_cvt_pk_bf16_f32 v117, v114, v115
	ds_write_b32 v122, v116 offset:6976
	ds_write_b32 v122, v117 offset:7264
	v_mul_f32_e32 v104, v32, v76
	v_mul_f32_e32 v105, v34, v78
	v_mul_f32_e32 v106, v33, v77
	v_mul_f32_e32 v107, v35, v79
	v_mov_b32_dpp v108, v104 quad_perm:[1,0,3,2] row_mask:0xf bank_mask:0xf
	v_mov_b32_dpp v109, v105 quad_perm:[1,0,3,2] row_mask:0xf bank_mask:0xf
	v_mov_b32_dpp v110, v106 quad_perm:[1,0,3,2] row_mask:0xf bank_mask:0xf
	v_mov_b32_dpp v111, v107 quad_perm:[1,0,3,2] row_mask:0xf bank_mask:0xf
	v_cndmask_b32_e32 v112, v109, v104, vcc
	v_cndmask_b32_e32 v113, v105, v108, vcc
	v_cndmask_b32_e32 v114, v111, v106, vcc
	v_cndmask_b32_e32 v115, v107, v110, vcc
	v_cvt_pk_bf16_f32 v116, v112, v113
	v_cvt_pk_bf16_f32 v117, v114, v115
	ds_write_b32 v122, v116 offset:128
	ds_write_b32 v122, v117 offset:416
	v_mul_f32_e32 v104, v36, v72
	v_mul_f32_e32 v105, v38, v74
	v_mul_f32_e32 v106, v37, v73
	v_mul_f32_e32 v107, v39, v75
	v_mov_b32_dpp v108, v104 quad_perm:[1,0,3,2] row_mask:0xf bank_mask:0xf
	v_mov_b32_dpp v109, v105 quad_perm:[1,0,3,2] row_mask:0xf bank_mask:0xf
	v_mov_b32_dpp v110, v106 quad_perm:[1,0,3,2] row_mask:0xf bank_mask:0xf
	v_mov_b32_dpp v111, v107 quad_perm:[1,0,3,2] row_mask:0xf bank_mask:0xf
	v_cndmask_b32_e32 v112, v109, v104, vcc
	v_cndmask_b32_e32 v113, v105, v108, vcc
	v_cndmask_b32_e32 v114, v111, v106, vcc
	v_cndmask_b32_e32 v115, v107, v110, vcc
	v_cvt_pk_bf16_f32 v116, v112, v113
	v_cvt_pk_bf16_f32 v117, v114, v115
	ds_write_b32 v122, v116 offset:2432
	ds_write_b32 v122, v117 offset:2720
	v_mul_f32_e32 v104, v40, v68
	v_mul_f32_e32 v105, v42, v70
	v_mul_f32_e32 v106, v41, v69
	v_mul_f32_e32 v107, v43, v71
	v_mov_b32_dpp v108, v104 quad_perm:[1,0,3,2] row_mask:0xf bank_mask:0xf
	v_mov_b32_dpp v109, v105 quad_perm:[1,0,3,2] row_mask:0xf bank_mask:0xf
	v_mov_b32_dpp v110, v106 quad_perm:[1,0,3,2] row_mask:0xf bank_mask:0xf
	v_mov_b32_dpp v111, v107 quad_perm:[1,0,3,2] row_mask:0xf bank_mask:0xf
	v_cndmask_b32_e32 v112, v109, v104, vcc
	v_cndmask_b32_e32 v113, v105, v108, vcc
	v_cndmask_b32_e32 v114, v111, v106, vcc
	v_cndmask_b32_e32 v115, v107, v110, vcc
	v_cvt_pk_bf16_f32 v116, v112, v113
	v_cvt_pk_bf16_f32 v117, v114, v115
	ds_write_b32 v122, v116 offset:4736
	ds_write_b32 v122, v117 offset:5024
	v_mul_f32_e32 v104, v44, v64
	v_mul_f32_e32 v105, v46, v66
	v_mul_f32_e32 v106, v45, v65
	v_mul_f32_e32 v107, v47, v67
	v_mov_b32_dpp v108, v104 quad_perm:[1,0,3,2] row_mask:0xf bank_mask:0xf
	v_mov_b32_dpp v109, v105 quad_perm:[1,0,3,2] row_mask:0xf bank_mask:0xf
	v_mov_b32_dpp v110, v106 quad_perm:[1,0,3,2] row_mask:0xf bank_mask:0xf
	v_mov_b32_dpp v111, v107 quad_perm:[1,0,3,2] row_mask:0xf bank_mask:0xf
	v_cndmask_b32_e32 v112, v109, v104, vcc
	v_cndmask_b32_e32 v113, v105, v108, vcc
	v_cndmask_b32_e32 v114, v111, v106, vcc
	v_cndmask_b32_e32 v115, v107, v110, vcc
	v_cvt_pk_bf16_f32 v116, v112, v113
	v_cvt_pk_bf16_f32 v117, v114, v115
	ds_write_b32 v122, v116 offset:7040
	ds_write_b32 v122, v117 offset:7328
	v_mul_f32_e32 v104, v16, v76
	v_mul_f32_e32 v105, v18, v78
	v_mul_f32_e32 v106, v17, v77
	v_mul_f32_e32 v107, v19, v79
	v_mov_b32_dpp v108, v104 quad_perm:[1,0,3,2] row_mask:0xf bank_mask:0xf
	v_mov_b32_dpp v109, v105 quad_perm:[1,0,3,2] row_mask:0xf bank_mask:0xf
	v_mov_b32_dpp v110, v106 quad_perm:[1,0,3,2] row_mask:0xf bank_mask:0xf
	v_mov_b32_dpp v111, v107 quad_perm:[1,0,3,2] row_mask:0xf bank_mask:0xf
	v_cndmask_b32_e32 v112, v109, v104, vcc
	v_cndmask_b32_e32 v113, v105, v108, vcc
	v_cndmask_b32_e32 v114, v111, v106, vcc
	v_cndmask_b32_e32 v115, v107, v110, vcc
	v_cvt_pk_bf16_f32 v116, v112, v113
	v_cvt_pk_bf16_f32 v117, v114, v115
	ds_write_b32 v122, v116 offset:192
	ds_write_b32 v122, v117 offset:480
	v_mul_f32_e32 v104, v20, v72
	v_mul_f32_e32 v105, v22, v74
	v_mul_f32_e32 v106, v21, v73
	v_mul_f32_e32 v107, v23, v75
	v_mov_b32_dpp v108, v104 quad_perm:[1,0,3,2] row_mask:0xf bank_mask:0xf
	v_mov_b32_dpp v109, v105 quad_perm:[1,0,3,2] row_mask:0xf bank_mask:0xf
; __device__ __forceinline__ int crow(int r, int hi) { return (r & 3) + 8 * (r >> 2) + 4 * hi; }
; __device__ __forceinline__ unsigned cvtpk(float lo, float hi) { return pg8::cvt_pk_bf16(lo, hi); }
; #define KARG(T_, i) ((T_)kargp(i))
; __device__ __forceinline__ void attn_block(const BlockRef& cur, const BlockRef& nxt, char* lds, Seam& S) {
;     ...
;     for (int r = 0; r < 16; ++r) rli[r] = __builtin_amdgcn_rcpf(li_l[crow(r, hi)]);
;     bf16* Ow = cur.O + (size_t)(wid * QBLK) * D;
; #pragma unroll
;     for (int r = 0; r < 16; ++r) { const int orow = crow(r, hi);
; #pragma unroll
;         for (int d0 = 0; d0 < 4; ++d0) { const float v = o[d0][r] * rli[r];
;             const float vn = __shfl_xor(v, 1);
;             if ((r32 & 1) == 0) __builtin_nontemporal_store(cvtpk(v, vn), (unsigned*)(Ow + (size_t)orow * D + d0 * 32 + r32)); } }
;     __syncthreads();
; __global__ void __launch_bounds__(NTHR, 2) mega_fwd(Args args) {
;     ...
;                 if (sub == 7) {
;                     asm volatile("s_waitcnt vmcnt(0)" ::: "memory"); __syncthreads();
;                     float lam;
;                     { const float* lq1 = KARG(const float*, 13); const float* lk1 = KARG(const float*, 14); const float* lq2 = KARG(const float*, 15); const float* lk2 = KARG(const float*, 16);
;                       lam = __expf(wave_sum(lq1[lane] * lk1[lane] + lq1[lane + 64] * lk1[lane + 64])) - __expf(wave_sum(lq2[lane] * lk2[lane] + lq2[lane + 64] * lk2[lane + 64])) + 0.2f; }
;                     const int l16 = lane & 15, rq = lane >> 4;
;                     const float* subln_g = KARG(const float*, 17);
;                     f32x4 sg[2][2];
; #pragma unroll
;                     for (int vh = 0; vh < 2; ++vh) { sg[vh][0] = *(const f32x4*)(subln_g + vh * 128 + 8 * l16) * 0.8f; sg[vh][1] = *(const f32x4*)(subln_g + vh * 128 + 8 * l16 + 4) * 0.8f; }
;                     const int bh_ = si >> 4, j_ = si & 15, b_ = bh_ >> 2, h_ = bh_ & 3;
	v_mov_b32_dpp v110, v106 quad_perm:[1,0,3,2] row_mask:0xf bank_mask:0xf
	v_mov_b32_dpp v111, v107 quad_perm:[1,0,3,2] row_mask:0xf bank_mask:0xf
	v_cndmask_b32_e32 v112, v109, v104, vcc
	v_cndmask_b32_e32 v113, v105, v108, vcc
	v_cndmask_b32_e32 v114, v111, v106, vcc
	v_cndmask_b32_e32 v115, v107, v110, vcc
	v_cvt_pk_bf16_f32 v116, v112, v113
	v_cvt_pk_bf16_f32 v117, v114, v115
	ds_write_b32 v122, v116 offset:2496
	ds_write_b32 v122, v117 offset:2784
	v_mul_f32_e32 v104, v24, v68
	v_mul_f32_e32 v105, v26, v70
	v_mul_f32_e32 v106, v25, v69
	v_mul_f32_e32 v107, v27, v71
	v_mov_b32_dpp v108, v104 quad_perm:[1,0,3,2] row_mask:0xf bank_mask:0xf
	v_mov_b32_dpp v109, v105 quad_perm:[1,0,3,2] row_mask:0xf bank_mask:0xf
	v_mov_b32_dpp v110, v106 quad_perm:[1,0,3,2] row_mask:0xf bank_mask:0xf
	v_mov_b32_dpp v111, v107 quad_perm:[1,0,3,2] row_mask:0xf bank_mask:0xf
	v_cndmask_b32_e32 v112, v109, v104, vcc
	v_cndmask_b32_e32 v113, v105, v108, vcc
	v_cndmask_b32_e32 v114, v111, v106, vcc
	v_cndmask_b32_e32 v115, v107, v110, vcc
	v_cvt_pk_bf16_f32 v116, v112, v113
	v_cvt_pk_bf16_f32 v117, v114, v115
	ds_write_b32 v122, v116 offset:4800
	ds_write_b32 v122, v117 offset:5088
	v_mul_f32_e32 v104, v28, v64
	v_mul_f32_e32 v105, v30, v66
	v_mul_f32_e32 v106, v29, v65
	v_mul_f32_e32 v107, v31, v67
	v_mov_b32_dpp v108, v104 quad_perm:[1,0,3,2] row_mask:0xf bank_mask:0xf
	v_mov_b32_dpp v109, v105 quad_perm:[1,0,3,2] row_mask:0xf bank_mask:0xf
	v_mov_b32_dpp v110, v106 quad_perm:[1,0,3,2] row_mask:0xf bank_mask:0xf
	v_mov_b32_dpp v111, v107 quad_perm:[1,0,3,2] row_mask:0xf bank_mask:0xf
	v_cndmask_b32_e32 v112, v109, v104, vcc
	v_cndmask_b32_e32 v113, v105, v108, vcc
	v_cndmask_b32_e32 v114, v111, v106, vcc
	v_cndmask_b32_e32 v115, v107, v110, vcc
	v_cvt_pk_bf16_f32 v116, v112, v113
	v_cvt_pk_bf16_f32 v117, v114, v115
	ds_write_b32 v122, v116 offset:7104
	ds_write_b32 v122, v117 offset:7392
	s_waitcnt lgkmcnt(0)
	ds_read_b128 v[160:163], v123
	ds_read_b128 v[164:167], v123 offset:1152
	ds_read_b128 v[168:171], v123 offset:2304
	ds_read_b128 v[172:175], v123 offset:3456
	ds_read_b128 v[176:179], v123 offset:4608
	ds_read_b128 v[180:183], v123 offset:5760
	ds_read_b128 v[184:187], v123 offset:6912
	ds_read_b128 v[188:191], v123 offset:8064
	s_waitcnt lgkmcnt(7)
	global_store_dwordx4 v[124:125], v[160:163], off nt
	s_waitcnt lgkmcnt(6)
	global_store_dwordx4 v[124:125], v[164:167], off offset:1024 nt
	s_waitcnt lgkmcnt(5)
	global_store_dwordx4 v[124:125], v[168:171], off offset:2048 nt
	s_waitcnt lgkmcnt(4)
	global_store_dwordx4 v[124:125], v[172:175], off offset:3072 nt
	s_waitcnt lgkmcnt(3)
	global_store_dwordx4 v[126:127], v[176:179], off nt
	s_waitcnt lgkmcnt(2)
	global_store_dwordx4 v[126:127], v[180:183], off offset:1024 nt
	s_waitcnt lgkmcnt(1)
	global_store_dwordx4 v[126:127], v[184:187], off offset:2048 nt
	s_waitcnt lgkmcnt(0)
	global_store_dwordx4 v[126:127], v[188:191], off offset:3072 nt
	v_and_b32_e32 v80, 64, v205
	v_add_u32_e32 v82, 64, v80
	v_xor_b32_e32 v76, 1, v205
	v_lshlrev_b32_e32 v76, 2, v76
	s_cmp_lg_u32 s77, 7
	s_waitcnt lgkmcnt(0)
	s_barrier
	s_cbranch_scc1 .LBB0_485
	s_mov_b64 s[38:39], s[0:1]
	s_waitcnt vmcnt(0)
	s_barrier
	s_load_dwordx2 s[42:43], s[38:39], 0x68
	s_mov_b64 s[38:39], s[0:1]
	s_load_dwordx2 s[50:51], s[38:39], 0x70
	s_mov_b64 s[38:39], s[0:1]
	s_load_dwordx2 s[40:41], s[38:39], 0x78
	s_mov_b64 s[38:39], s[0:1]
	s_load_dwordx2 s[38:39], s[38:39], 0x80
	s_waitcnt lgkmcnt(0)
	global_load_dword v0, v214, s[42:43]
	global_load_dword v1, v214, s[50:51]
	global_load_dword v2, v214, s[42:43] offset:256
	global_load_dword v3, v214, s[50:51] offset:256
	global_load_dword v4, v214, s[40:41]
	global_load_dword v5, v214, s[38:39]
	global_load_dword v6, v214, s[40:41] offset:256
	global_load_dword v7, v214, s[38:39] offset:256
	s_mov_b64 s[38:39], s[0:1]
	s_waitcnt vmcnt(4)
	v_mul_f32_e32 v2, v2, v3
	v_fmac_f32_e32 v2, v0, v1
	ds_bpermute_b32 v0, v76, v2
	v_xor_b32_e32 v1, 2, v205
	v_cmp_lt_i32_e32 vcc, v1, v82
	s_waitcnt vmcnt(0)
	v_mul_f32_e32 v6, v6, v7
	v_fmac_f32_e32 v6, v4, v5
	v_cndmask_b32_e32 v1, v205, v1, vcc
	s_waitcnt lgkmcnt(0)
	v_add_f32_e32 v0, v2, v0
	v_lshlrev_b32_e32 v20, 2, v1
	ds_bpermute_b32 v1, v20, v0
	ds_bpermute_b32 v4, v76, v6
	s_waitcnt lgkmcnt(1)
	v_add_f32_e32 v0, v0, v1
	v_xor_b32_e32 v1, 4, v205
	v_cmp_lt_i32_e32 vcc, v1, v82
	s_waitcnt lgkmcnt(0)
	v_add_f32_e32 v4, v6, v4
	ds_bpermute_b32 v5, v20, v4
	v_cndmask_b32_e32 v1, v205, v1, vcc
	v_lshlrev_b32_e32 v21, 2, v1
	ds_bpermute_b32 v1, v21, v0
	s_waitcnt lgkmcnt(1)
	v_add_f32_e32 v4, v4, v5
	ds_bpermute_b32 v5, v21, v4
	s_waitcnt lgkmcnt(1)
	v_add_f32_e32 v0, v0, v1
	v_xor_b32_e32 v1, 8, v205
	v_cmp_lt_i32_e32 vcc, v1, v82
	s_waitcnt lgkmcnt(0)
	v_add_f32_e32 v4, v4, v5
	v_cndmask_b32_e32 v1, v205, v1, vcc
	v_lshlrev_b32_e32 v22, 2, v1
	ds_bpermute_b32 v1, v22, v0
	ds_bpermute_b32 v5, v22, v4
	s_waitcnt lgkmcnt(1)
	v_add_f32_e32 v0, v0, v1
	v_xor_b32_e32 v1, 16, v205
	v_cmp_lt_i32_e32 vcc, v1, v82
	s_waitcnt lgkmcnt(0)
	v_add_f32_e32 v4, v4, v5
	v_cndmask_b32_e32 v1, v205, v1, vcc
	v_lshlrev_b32_e32 v2, 2, v1
	ds_bpermute_b32 v1, v2, v0
	ds_bpermute_b32 v2, v2, v4
	s_waitcnt lgkmcnt(1)
	v_add_f32_e32 v0, v0, v1
	v_xor_b32_e32 v1, 32, v205
	v_cmp_lt_i32_e32 vcc, v1, v82
	s_waitcnt lgkmcnt(0)
	v_add_f32_e32 v2, v4, v2
	v_cndmask_b32_e32 v1, v205, v1, vcc
	v_lshlrev_b32_e32 v3, 2, v1
	ds_bpermute_b32 v1, v3, v0
	ds_bpermute_b32 v3, v3, v2
	s_andn2_b64 vcc, exec, s[24:25]
	s_cbranch_vccnz .LBB0_485
	s_load_dwordx2 s[38:39], s[38:39], 0x88
	s_waitcnt lgkmcnt(0)
	v_add_f32_e32 v0, v0, v1
	v_add_f32_e32 v1, v2, v3
	v_mul_f32_e32 v0, 0x3fb8aa3b, v0
	v_mul_f32_e32 v1, 0x3fb8aa3b, v1
	global_load_dwordx4 v[8:11], v215, s[38:39] offset:512
	global_load_dwordx4 v[4:7], v215, s[38:39] offset:528
	global_load_dwordx4 v[16:19], v215, s[38:39]
	global_load_dwordx4 v[12:15], v215, s[38:39] offset:16
	v_exp_f32_e32 v0, v0
	v_exp_f32_e32 v1, v1
	s_bfe_u32 s38, s66, 0x20004
	s_ashr_i32 s39, s66, 6
	s_lshl_b32 s40, s66, 8
	v_sub_f32_e32 v0, v0, v1
	s_lshl_b32 s42, s39, 17
	s_lshl_b32 s43, s38, 15
	v_add_f32_e32 v0, 0x3e4ccccd, v0
	s_and_b32 s40, s40, 0xf00
	s_or_b32 s42, s43, s42
	s_lshl_b32 s43, s39, 13
	s_lshl_b32 s38, s38, 9
	s_mov_b32 s39, s48
	s_xor_b32 s41, s40, 0x1f00
	v_mov_b32_e32 v1, v0
	v_readlane_b32 s49, v254, 59
	s_waitcnt vmcnt(3)
	v_pk_mul_f32 v[8:9], v[8:9], s[28:29] op_sel_hi:[1,0]
	s_waitcnt vmcnt(2)
	v_pk_mul_f32 v[2:3], v[6:7], s[28:29] op_sel_hi:[1,0]
	v_pk_mul_f32 v[4:5], v[4:5], s[28:29] op_sel_hi:[1,0]
	v_pk_mul_f32 v[6:7], v[10:11], s[28:29] op_sel_hi:[1,0]
	s_waitcnt vmcnt(0)
	v_pk_mul_f32 v[10:11], v[14:15], s[28:29] op_sel_hi:[1,0]
	v_pk_mul_f32 v[12:13], v[12:13], s[28:29] op_sel_hi:[1,0]
	v_pk_mul_f32 v[14:15], v[18:19], s[28:29] op_sel_hi:[1,0]
	v_pk_mul_f32 v[16:17], v[16:17], s[28:29] op_sel_hi:[1,0]
	v_lshl_add_u64 v[18:19], v[198:199], 0, s[38:39]

; #define PG8_WAIT_V(n) asm volatile("s_waitcnt vmcnt(" #n ")" ::: "memory")
;     __host__ __device__ bool next(int i, Unit& u) const {
;         const long L = (long)i * G + c; if (L >= nwg) return false;
;         int wgid = (int)L; { const int q = nwg / NXCD, r = nwg % NXCD, xcd = wgid % NXCD, off = wgid / NXCD; wgid = (xcd < r ? xcd * (q + 1) : r * (q + 1) + (xcd - r) * q) + off; }
;         const int nig = wgm * nN, gid = wgid / nig, fm = gid * wgm, gsz = (nM - fm) < wgm ? (nM - fm) : wgm;
;         u.pm = fm + ((wgid % nig) % gsz); u.pn = (wgid % nig) / gsz; if (rev) u.pm = nM - 1 - u.pm; return true;
; template <class Epi, class Sched, bool ALIGN_EPI = false, bool SP2 = false>
; __device__ __forceinline__ void gemm_phase(PG8_LAS unsigned char* lds, const Gemm g, const Sched& S, const Epi& E) {
;     ...
;     const int tid = tid_, wid = __builtin_amdgcn_readfirstlane(tid >> 6), lane = tid & 63, wr = wid >> 2, wc = wid & 3, fr = lane & 15, fq = lane >> 4;
;     const int K = g.K, nt = K / BK;
;     unsigned voffA[2], voffB[2];
; #pragma unroll
;     for (int i = 0; i < 2; ++i) { int R, C; stage_rc(tid * 16 + i * 8192, R, C); const int Rb = Epi::PERM ? ((R & ~31) + perm32(R & 31)) : R;
;         voffA[i] = (unsigned)(R * K + C) * 2u; voffB[i] = (unsigned)(Rb * K + C) * 2u; }
;     const size_t kstep = (size_t)(BK * 2);
;     const size_t hstep = (size_t)HALF * K * 2;
;     const size_t tstep = 2 * hstep;
;     const unsigned ldsw = (unsigned)wid * 1024u;
;     const int aoff = lds_byte(wr * 64 + fr, fq * 8), boff = lds_byte(wc * 32 + fr, fq * 8);
;     ...
;     Unit cur, nxt; int ui = 0;
;     if (!S.next(0, cur)) return;
;     f32x4 acc[2][2][4][2];
; #pragma unroll
;     for (int a = 0; a < 2; ++a)
; #pragma unroll
;         for (int b = 0; b < 2; ++b)
; #pragma unroll
;             for (int m = 0; m < 4; ++m)
; #pragma unroll
;                 for (int n = 0; n < 2; ++n) acc[a][b][m][n] = (f32x4){0.f, 0.f, 0.f, 0.f};
;     bf16x8 At[4][2], B0[2][2], B1[2][2];
;     const char* cA = (const char*)g.A + (size_t)cur.pm * tstep; const char* cB = (const char*)g.Bt + (size_t)cur.pn * tstep;
;     S.a_ready(cur);
;     if constexpr (SP2) {
;         PG8_STAGE(PG8_SB(0, 0), cB, voffB); PG8_STAGE(PG8_SB(0, 1), cB + hstep, voffB); PG8_STAGE(PG8_SA(0, 0), cA, voffA); PG8_STAGE(PG8_SA(0, 1), cA + hstep, voffA);
;         if (wr == 1) PG8_BAR;
;         PG8_WAIT_V(2); PG8_BAR;
.LBB0_540:
	s_or_b64 exec, exec, s[14:15]
	s_nop 0
	s_nop 0
	s_nop 0
	s_nop 0
	s_nop 0
	s_nop 0
	s_cmpk_lt_i32 s2, 0x400
	s_mov_b64 s[22:23], s[0:1]
	s_mov_b64 s[16:17], s[0:1]
	s_mov_b64 s[24:25], s[0:1]
	s_mov_b64 s[18:19], s[0:1]
	s_mov_b64 s[14:15], s[0:1]
	s_waitcnt lgkmcnt(0)
	s_barrier
	s_cselect_b64 s[48:49], -1, 0
	s_lshr_b32 s13, s33, 29
	s_add_i32 s13, s2, s13
	s_load_dwordx2 s[14:15], s[14:15], 0xc8
	s_ashr_i32 s56, s13, 3
	s_and_b32 s13, s13, -8
	s_load_dwordx2 s[20:21], s[16:17], 0xc8
	s_nop 0
	s_load_dwordx2 s[18:19], s[18:19], 0xc8
	s_mov_b64 s[16:17], s[0:1]
	s_sub_i32 s59, s2, s13
	s_cmp_lt_i32 s59, 0
	s_load_dwordx2 s[16:17], s[16:17], 0xc8
	s_cselect_b64 s[42:43], -1, 0
	s_lshl_b32 s57, s59, 7
	s_waitcnt lgkmcnt(0)
	s_add_u32 s14, s14, 0x2f800000
	s_addc_u32 s15, s15, 0
	s_waitcnt vmcnt(27)
	v_mov_b32_e32 v14, v216
	s_cmpk_gt_i32 s2, 0x3ff
	s_mul_i32 s58, s59, 0x81
	s_nop 0
	v_readfirstlane_b32 s28, v14
	s_cbranch_scc1 .LBB0_560
	v_lshlrev_b32_e32 v0, 4, v14
	v_add_u32_e32 v1, 0x2000, v0
	v_ashrrev_i32_e32 v2, 31, v1
	v_lshrrev_b32_e32 v2, 22, v2
	v_add_u32_e32 v2, v1, v2
	v_ashrrev_i32_e32 v8, 10, v2
	v_mul_i32_i24_e32 v2, 0x400, v8
	v_sub_u32_e32 v1, v1, v2
	v_lshrrev_b32_e32 v2, 4, v1
	v_bitop3_b32 v1, v2, v1, 32 bitop3:0x6c
	v_ashrrev_i32_e32 v2, 31, v1
	s_load_dwordx2 s[22:23], s[22:23], 0xc8
	s_nop 0
	s_load_dwordx2 s[24:25], s[24:25], 0xc8
	v_lshrrev_b32_e32 v2, 26, v2
	v_add_u32_e32 v2, v1, v2
	v_lshlrev_b32_e32 v3, 3, v8
	v_ashrrev_i32_e32 v9, 6, v2
	v_and_b32_e32 v3, -16, v3
	v_add_u32_e32 v3, v9, v3
	s_waitcnt lgkmcnt(0)
	s_add_u32 s13, s22, 0x3b800000
	v_and_b32_e32 v4, 3, v9
	s_mov_b32 s22, 0x1fffe0
	v_lshrrev_b32_e32 v5, 2, v3
	v_lshlrev_b32_e32 v6, 1, v3
	v_and_b32_e32 v2, 0xc0, v2
	v_and_or_b32 v4, v3, s22, v4
	v_and_b32_e32 v5, 4, v5
	v_and_b32_e32 v6, 24, v6
	v_sub_u32_e32 v1, v1, v2
	v_mov_b32_e32 v2, 1
	v_or3_b32 v4, v4, v5, v6
	v_lshlrev_b32_e32 v5, 5, v8
	v_ashrrev_i16_sdwa v1, v2, sext(v1) dst_sel:DWORD dst_unused:UNUSED_PAD src0_sel:DWORD src1_sel:BYTE_0
	v_and_b32_e32 v5, 32, v5
	v_bfe_i32 v10, v1, 0, 16
	v_add_lshl_u32 v1, v5, v10, 1
	s_waitcnt vmcnt(6)
	v_lshl_add_u32 v152, v4, 11, v1
	v_lshl_add_u32 v154, v3, 11, v1
	v_bfe_i32 v1, v14, 27, 1
	v_lshrrev_b32_e32 v1, 22, v1
	v_add_u32_e32 v1, v0, v1
	v_and_b32_e32 v1, 0xfffffc00, v1
	v_sub_u32_e32 v0, v0, v1
	v_lshrrev_b32_e32 v1, 4, v0
	v_ashrrev_i32_e32 v3, 31, v14
	v_bitop3_b32 v0, v1, v0, 32 bitop3:0x6c
	v_lshrrev_b32_e32 v3, 26, v3
	v_ashrrev_i32_e32 v1, 31, v0
	v_add_u32_e32 v3, v14, v3
	s_addc_u32 s47, s23, 0
	v_lshrrev_b32_e32 v1, 26, v1
	v_ashrrev_i32_e32 v12, 6, v3
	s_add_u32 s60, s24, 0x2600000
	v_add_u32_e32 v1, v0, v1
	v_lshlrev_b32_e32 v3, 3, v12
	s_addc_u32 s61, s25, 0
	s_ashr_i32 s26, s28, 6
	v_ashrrev_i32_e32 v11, 6, v1
	v_and_b32_e32 v3, -16, v3
	s_ashr_i32 s27, s28, 8
	s_lshl_b32 s62, s26, 10
	v_add_u32_e32 v3, v11, v3
	v_and_b32_e32 v4, 3, v11
	v_and_or_b32 v4, v3, s22, v4
	s_and_b64 s[22:23], s[42:43], exec
	s_cselect_b32 s22, s58, s57
	s_add_i32 s22, s22, s56
	s_ashr_i32 s23, s22, 31
	s_lshr_b32 s23, s23, 27
	s_add_i32 s23, s22, s23
	s_ashr_i32 s24, s23, 5
	s_and_b32 s23, s23, 0xffe0
	s_sub_i32 s22, s22, s23
	s_bfe_i32 s23, s22, 0x80000
	s_bfe_u32 s23, s23, 0x2000d
	s_add_i32 s23, s22, s23
	s_lshl_b32 s25, s24, 2
	s_bfe_i32 s24, s23, 0x80000
	s_and_b32 s23, s23, 0xfc
	s_sub_i32 s22, s22, s23
	s_sext_i32_i16 s24, s24
	s_sext_i32_i8 s22, s22
	v_lshrrev_b32_e32 v5, 2, v3
	v_lshlrev_b32_e32 v6, 1, v3
	v_and_b32_e32 v1, 0xc0, v1
	s_lshr_b32 s24, s24, 2
	s_add_i32 s44, s25, s22
	v_and_b32_e32 v5, 4, v5
	v_and_b32_e32 v6, 24, v6
	v_sub_u32_e32 v0, v0, v1
	s_ashr_i32 s45, s44, 31
	s_bfe_i64 s[30:31], s[24:25], 0x100000
	v_or3_b32 v4, v4, v5, v6
	v_lshlrev_b32_e32 v5, 5, v12
	v_ashrrev_i16_sdwa v0, v2, sext(v0) dst_sel:DWORD dst_unused:UNUSED_PAD src0_sel:DWORD src1_sel:BYTE_0
	s_lshl_b64 s[22:23], s[44:45], 19
	s_lshl_b64 s[30:31], s[30:31], 19
	v_and_b32_e32 v5, 32, v5
	v_bfe_i32 v13, v0, 0, 16
	s_add_u32 s52, s60, s30
	v_add_lshl_u32 v0, v5, v13, 1
	s_addc_u32 s53, s61, s31
	s_add_i32 s63, s62, 0
	v_lshl_add_u32 v156, v4, 11, v0
	s_add_i32 m0, s63, 0x10000
	v_lshl_add_u32 v158, v3, 11, v0
	global_load_lds_dwordx4 v156, s[52:53]
	s_add_i32 m0, s63, 0x12000
	s_add_u32 s30, s52, 0x40000
	global_load_lds_dwordx4 v152, s[52:53]
	s_addc_u32 s31, s53, 0
	s_add_i32 m0, s63, 0x14000
	v_mov_b32_e32 v157, 0
	global_load_lds_dwordx4 v156, s[30:31]
	s_add_i32 m0, s63, 0x16000
	s_add_u32 s50, s13, s22
	s_addc_u32 s51, s47, s23
	s_add_i32 s64, s63, 0x2000
	global_load_lds_dwordx4 v152, s[30:31]
	s_mov_b32 m0, s63
	s_add_u32 s22, s50, 0x40000
	global_load_lds_dwordx4 v158, s[50:51]
	s_mov_b32 m0, s64
	s_addc_u32 s23, s51, 0
	s_add_i32 s65, s63, 0x4000
	global_load_lds_dwordx4 v154, s[50:51]
	s_mov_b32 m0, s65
	s_add_i32 s66, s63, 0x6000
	global_load_lds_dwordx4 v158, s[22:23]
	s_mov_b32 m0, s66
	v_mov_b32_e32 v153, v157
	global_load_lds_dwordx4 v154, s[22:23]
	v_mov_b32_e32 v159, v157
	v_mov_b32_e32 v155, v157
	s_cmp_eq_u32 s27, 1
	v_lshl_add_u64 v[6:7], s[52:53], 0, v[156:157]
	v_lshl_add_u64 v[4:5], s[52:53], 0, v[152:153]
	v_lshl_add_u64 v[0:1], s[50:51], 0, v[158:159]
	s_cselect_b64 s[22:23], -1, 0
	s_cmp_lg_u32 s27, 1
	v_lshl_add_u64 v[2:3], s[50:51], 0, v[154:155]
	s_cbranch_scc1 .LBB0_543
	s_barrier
